# EpiResid epilogues pipelined (7 steps of loads in flight) + half of the workgroups (bid bit 3) start EpiResid GEMM phases 4 sleeps late to de-synchronise epilogue HBM bursts
# baseline (speedup 1.0000x reference)
;     __device__ bool next(int i, Unit& u) const {
;         const long L = (long)i * G + c; if (L >= nwg) return false;
;         int wgid = (int)L; { const int q = nwg / NXCD, r = nwg % NXCD, xcd = wgid % NXCD, off = wgid / NXCD; wgid = (xcd < r ? xcd * (q + 1) : r * (q + 1) + (xcd - r) * q) + off; }
;         const int nig = WGM * nN, gid = wgid / nig, fm = gid * WGM, gsz = (nM - fm) < WGM ? (nM - fm) : WGM;
; __global__ void __launch_bounds__(NTHREADS, 2) fwd_kernel(Args args) {
;     ...
;     if (IN(2)) { pg8::StdOrder S; S.init(T, D, G, bid, DFF, DFF, D, 256); pg8::EpiResid E{x, out, 0.5f}; pg8::gemm_phase(lds, HB, WDN1, DFF, DFF, DFF, S, E); }
.LBB0_180:
	v_writelane_b32 v244, s83, 13
	v_writelane_b32 v244, s64, 14
	s_cmp_lt_i32 s94, 3
	s_cselect_b64 s[6:7], -1, 0
	v_writelane_b32 v244, s65, 15
	v_writelane_b32 v244, s80, 16
	s_and_b64 s[0:1], s[6:7], s[2:3]
	s_andn2_b64 vcc, exec, s[0:1]
	v_writelane_b32 v244, s81, 17
	v_writelane_b32 v244, s66, 18
	s_nop 1
	v_writelane_b32 v244, s67, 19
	v_writelane_b32 v244, s44, 20
	s_nop 1
	v_writelane_b32 v244, s45, 21
	s_cbranch_vccnz .LBB0_206
	s_cmpk_gt_i32 s83, 0x3ff
	v_readfirstlane_b32 s0, v177
	s_cbranch_scc1 .LBB0_206
	s_and_b32 s98, s83, 8
	s_cmp_eq_u32 s98, 0
	s_cbranch_scc1 .Ldly_skip_0
	s_mov_b32 s98, 4
.Ldly_loop_0:
	s_sleep 127
	s_sub_u32 s98, s98, 1
	s_cmp_lg_u32 s98, 0
	s_cbranch_scc1 .Ldly_loop_0
.Ldly_skip_0:
	s_ashr_i32 s1, s83, 31
	s_mov_b32 s44, s1
	s_lshr_b32 s1, s1, 29
	s_add_i32 s1, s83, s1
	s_and_b32 s2, s1, -8
	s_sub_i32 s5, s83, s2
	s_cmp_gt_i32 s5, -1
	s_cbranch_scc0 .LBB0_184
	s_lshl_b32 s4, s5, 7
	s_mov_b64 s[2:3], 0
	s_branch .LBB0_185

;     __device__ __forceinline__ void operator()(Acc& acc, const Unit& u, int wr, int wc, int fr, int fq) const {
;         const size_t p0 = u.ooff + (size_t)(wr * 64 + fr) * D + wc * 32 + 8 * fq;
; #pragma unroll
;         for (int ai = 0; ai < 2; ++ai)
; #pragma unroll
;             for (int m = 0; m < 4; ++m)
; #pragma unroll
;                 for (int bj = 0; bj < 2; ++bj) {
;                     const size_t p = p0 + (size_t)(ai * 128 + m * 16) * D + bj * 128;
;                     const f32x4 r0 = *(const f32x4*)(R + p), r1 = *(const f32x4*)(R + p + 4);
;                     *(f32x4*)(O + p) = r0 + acc[ai][bj][m][0] * scale; *(f32x4*)(O + p + 4) = r1 + acc[ai][bj][m][1] * scale;
;                 }
.LBB0_202:
	v_lshl_add_u64 v[146:147], v[136:137], 0, s[80:81]
	v_readlane_b32 s16, v245, 3
	v_lshlrev_b64 v[146:147], 2, v[146:147]
	v_readlane_b32 s17, v245, 4
	v_readlane_b32 s18, v245, 5
	v_readlane_b32 s19, v245, 6
	v_lshl_add_u64 v[148:149], s[16:17], 0, v[146:147]
	v_readlane_b32 s20, v245, 7
	v_readlane_b32 s21, v245, 8
	v_readlane_b32 s22, v245, 9
	v_readlane_b32 s23, v245, 10
	v_readlane_b32 s16, v244, 28
	v_readlane_b32 s18, v244, 30
	v_readlane_b32 s19, v244, 31
	s_mov_b64 s[0:1], 0x100000
	v_readlane_b32 s24, v245, 11
	v_lshl_add_u64 v[146:147], s[18:19], 0, v[146:147]
	v_readlane_b32 s25, v245, 12
	v_readlane_b32 s26, v245, 13
	v_readlane_b32 s27, v245, 14
	v_readlane_b32 s28, v245, 15
	v_readlane_b32 s29, v245, 16
	v_readlane_b32 s30, v245, 17
	v_readlane_b32 s31, v245, 18
	v_readlane_b32 s17, v244, 29
	v_readlane_b32 s20, v244, 32
	v_readlane_b32 s21, v244, 33
	v_readlane_b32 s22, v244, 34
	v_readlane_b32 s23, v244, 35
	s_mov_b64 s[0:1], 0x160000
	s_andn2_b64 vcc, exec, s[2:3]
	s_mov_b64 s[2:3], -1
	s_mov_b64 s[98:99], 0x20000
	s_mov_b64 s[100:101], 0xa0000
	global_load_dwordx4 v[154:157], v[148:149], off
	global_load_dwordx4 v[158:161], v[148:149], off offset:16
	global_load_dwordx4 v[162:165], v[148:149], off offset:512
	global_load_dwordx4 v[166:169], v[148:149], off offset:528
	v_lshl_add_u64 v[148:149], v[148:149], 0, s[98:99]
	global_load_dwordx4 v[170:173], v[148:149], off
	global_load_dwordx4 v[178:181], v[148:149], off offset:16
	global_load_dwordx4 v[182:185], v[148:149], off offset:512
	global_load_dwordx4 v[186:189], v[148:149], off offset:528
	v_lshl_add_u64 v[148:149], v[148:149], 0, s[98:99]
	global_load_dwordx4 v[190:193], v[148:149], off
	global_load_dwordx4 v[194:197], v[148:149], off offset:16
	global_load_dwordx4 v[198:201], v[148:149], off offset:512
	global_load_dwordx4 v[202:205], v[148:149], off offset:528
	v_lshl_add_u64 v[148:149], v[148:149], 0, s[98:99]
	global_load_dwordx4 v[206:209], v[148:149], off
	global_load_dwordx4 v[210:213], v[148:149], off offset:16
	s_waitcnt vmcnt(12)
	v_pk_fma_f32 v[124:125], v[124:125], 0.5, v[154:155] op_sel_hi:[1,0,1]
	v_pk_fma_f32 v[126:127], v[126:127], 0.5, v[156:157] op_sel_hi:[1,0,1]
	v_pk_fma_f32 v[120:121], v[120:121], 0.5, v[158:159] op_sel_hi:[1,0,1]
	v_pk_fma_f32 v[122:123], v[122:123], 0.5, v[160:161] op_sel_hi:[1,0,1]
	global_store_dwordx4 v[146:147], v[124:127], off
	global_store_dwordx4 v[146:147], v[120:123], off offset:16
	global_load_dwordx4 v[154:157], v[148:149], off offset:512
	global_load_dwordx4 v[158:161], v[148:149], off offset:528
	v_lshl_add_u64 v[148:149], v[148:149], 0, s[100:101]
	s_waitcnt vmcnt(14)
	v_pk_fma_f32 v[112:113], v[112:113], 0.5, v[162:163] op_sel_hi:[1,0,1]
	v_pk_fma_f32 v[114:115], v[114:115], 0.5, v[164:165] op_sel_hi:[1,0,1]
	v_pk_fma_f32 v[108:109], v[108:109], 0.5, v[166:167] op_sel_hi:[1,0,1]
	v_pk_fma_f32 v[110:111], v[110:111], 0.5, v[168:169] op_sel_hi:[1,0,1]
	global_store_dwordx4 v[146:147], v[112:115], off offset:512
	global_store_dwordx4 v[146:147], v[108:111], off offset:528
	v_lshl_add_u64 v[146:147], v[146:147], 0, s[98:99]
	global_load_dwordx4 v[162:165], v[148:149], off
	global_load_dwordx4 v[166:169], v[148:149], off offset:16
	s_waitcnt vmcnt(16)
	v_pk_fma_f32 v[116:117], v[116:117], 0.5, v[170:171] op_sel_hi:[1,0,1]
	v_pk_fma_f32 v[118:119], v[118:119], 0.5, v[172:173] op_sel_hi:[1,0,1]
	v_pk_fma_f32 v[104:105], v[104:105], 0.5, v[178:179] op_sel_hi:[1,0,1]
	v_pk_fma_f32 v[106:107], v[106:107], 0.5, v[180:181] op_sel_hi:[1,0,1]
	global_store_dwordx4 v[146:147], v[116:119], off
	global_store_dwordx4 v[146:147], v[104:107], off offset:16
	global_load_dwordx4 v[170:173], v[148:149], off offset:512
	global_load_dwordx4 v[178:181], v[148:149], off offset:528
	v_lshl_add_u64 v[148:149], v[148:149], 0, s[98:99]
	s_waitcnt vmcnt(18)
	v_pk_fma_f32 v[96:97], v[96:97], 0.5, v[182:183] op_sel_hi:[1,0,1]
	v_pk_fma_f32 v[98:99], v[98:99], 0.5, v[184:185] op_sel_hi:[1,0,1]
	v_pk_fma_f32 v[92:93], v[92:93], 0.5, v[186:187] op_sel_hi:[1,0,1]
	v_pk_fma_f32 v[94:95], v[94:95], 0.5, v[188:189] op_sel_hi:[1,0,1]
	global_store_dwordx4 v[146:147], v[96:99], off offset:512
	global_store_dwordx4 v[146:147], v[92:95], off offset:528
	v_lshl_add_u64 v[146:147], v[146:147], 0, s[98:99]
	global_load_dwordx4 v[182:185], v[148:149], off
	global_load_dwordx4 v[186:189], v[148:149], off offset:16
	s_waitcnt vmcnt(20)
	v_pk_fma_f32 v[100:101], v[100:101], 0.5, v[190:191] op_sel_hi:[1,0,1]
	v_pk_fma_f32 v[102:103], v[102:103], 0.5, v[192:193] op_sel_hi:[1,0,1]
	v_pk_fma_f32 v[88:89], v[88:89], 0.5, v[194:195] op_sel_hi:[1,0,1]
	v_pk_fma_f32 v[90:91], v[90:91], 0.5, v[196:197] op_sel_hi:[1,0,1]
	global_store_dwordx4 v[146:147], v[100:103], off
	global_store_dwordx4 v[146:147], v[88:91], off offset:16
	global_load_dwordx4 v[190:193], v[148:149], off offset:512
	global_load_dwordx4 v[194:197], v[148:149], off offset:528
	v_lshl_add_u64 v[148:149], v[148:149], 0, s[98:99]
	s_waitcnt vmcnt(22)
;     __device__ __forceinline__ void operator()(Acc& acc, const Unit& u, int wr, int wc, int fr, int fq) const {
;         const size_t p0 = u.ooff + (size_t)(wr * 64 + fr) * D + wc * 32 + 8 * fq;
; #pragma unroll
;         for (int ai = 0; ai < 2; ++ai)
; #pragma unroll
;             for (int m = 0; m < 4; ++m)
; #pragma unroll
;                 for (int bj = 0; bj < 2; ++bj) {
;                     const size_t p = p0 + (size_t)(ai * 128 + m * 16) * D + bj * 128;
;                     const f32x4 r0 = *(const f32x4*)(R + p), r1 = *(const f32x4*)(R + p + 4);
;                     *(f32x4*)(O + p) = r0 + acc[ai][bj][m][0] * scale; *(f32x4*)(O + p + 4) = r1 + acc[ai][bj][m][1] * scale;
;                 }
	v_pk_fma_f32 v[80:81], v[80:81], 0.5, v[198:199] op_sel_hi:[1,0,1]
	v_pk_fma_f32 v[82:83], v[82:83], 0.5, v[200:201] op_sel_hi:[1,0,1]
	v_pk_fma_f32 v[76:77], v[76:77], 0.5, v[202:203] op_sel_hi:[1,0,1]
	v_pk_fma_f32 v[78:79], v[78:79], 0.5, v[204:205] op_sel_hi:[1,0,1]
	global_store_dwordx4 v[146:147], v[80:83], off offset:512
	global_store_dwordx4 v[146:147], v[76:79], off offset:528
	v_lshl_add_u64 v[146:147], v[146:147], 0, s[98:99]
	global_load_dwordx4 v[198:201], v[148:149], off
	global_load_dwordx4 v[202:205], v[148:149], off offset:16
	s_waitcnt vmcnt(24)
	v_pk_fma_f32 v[84:85], v[84:85], 0.5, v[206:207] op_sel_hi:[1,0,1]
	v_pk_fma_f32 v[86:87], v[86:87], 0.5, v[208:209] op_sel_hi:[1,0,1]
	v_pk_fma_f32 v[72:73], v[72:73], 0.5, v[210:211] op_sel_hi:[1,0,1]
	v_pk_fma_f32 v[74:75], v[74:75], 0.5, v[212:213] op_sel_hi:[1,0,1]
	global_store_dwordx4 v[146:147], v[84:87], off
	global_store_dwordx4 v[146:147], v[72:75], off offset:16
	global_load_dwordx4 v[206:209], v[148:149], off offset:512
	global_load_dwordx4 v[210:213], v[148:149], off offset:528
	v_lshl_add_u64 v[148:149], v[148:149], 0, s[98:99]
	s_waitcnt vmcnt(24)
	v_pk_fma_f32 v[68:69], v[68:69], 0.5, v[154:155] op_sel_hi:[1,0,1]
	v_pk_fma_f32 v[70:71], v[70:71], 0.5, v[156:157] op_sel_hi:[1,0,1]
	v_pk_fma_f32 v[64:65], v[64:65], 0.5, v[158:159] op_sel_hi:[1,0,1]
	v_pk_fma_f32 v[66:67], v[66:67], 0.5, v[160:161] op_sel_hi:[1,0,1]
	global_store_dwordx4 v[146:147], v[68:71], off offset:512
	global_store_dwordx4 v[146:147], v[64:67], off offset:528
	v_lshl_add_u64 v[146:147], v[146:147], 0, s[100:101]
	global_load_dwordx4 v[154:157], v[148:149], off
	global_load_dwordx4 v[158:161], v[148:149], off offset:16
	s_waitcnt vmcnt(24)
	v_pk_fma_f32 v[60:61], v[60:61], 0.5, v[162:163] op_sel_hi:[1,0,1]
	v_pk_fma_f32 v[62:63], v[62:63], 0.5, v[164:165] op_sel_hi:[1,0,1]
	v_pk_fma_f32 v[56:57], v[56:57], 0.5, v[166:167] op_sel_hi:[1,0,1]
	v_pk_fma_f32 v[58:59], v[58:59], 0.5, v[168:169] op_sel_hi:[1,0,1]
	global_store_dwordx4 v[146:147], v[60:63], off
	global_store_dwordx4 v[146:147], v[56:59], off offset:16
	global_load_dwordx4 v[162:165], v[148:149], off offset:512
	global_load_dwordx4 v[166:169], v[148:149], off offset:528
	s_waitcnt vmcnt(24)
	v_pk_fma_f32 v[48:49], v[48:49], 0.5, v[170:171] op_sel_hi:[1,0,1]
	v_pk_fma_f32 v[50:51], v[50:51], 0.5, v[172:173] op_sel_hi:[1,0,1]
	v_pk_fma_f32 v[44:45], v[44:45], 0.5, v[178:179] op_sel_hi:[1,0,1]
	v_pk_fma_f32 v[46:47], v[46:47], 0.5, v[180:181] op_sel_hi:[1,0,1]
	global_store_dwordx4 v[146:147], v[48:51], off offset:512
	global_store_dwordx4 v[146:147], v[44:47], off offset:528
	v_lshl_add_u64 v[146:147], v[146:147], 0, s[98:99]
	s_waitcnt vmcnt(22)
	v_pk_fma_f32 v[52:53], v[52:53], 0.5, v[182:183] op_sel_hi:[1,0,1]
	v_pk_fma_f32 v[54:55], v[54:55], 0.5, v[184:185] op_sel_hi:[1,0,1]
	v_pk_fma_f32 v[40:41], v[40:41], 0.5, v[186:187] op_sel_hi:[1,0,1]
	v_pk_fma_f32 v[42:43], v[42:43], 0.5, v[188:189] op_sel_hi:[1,0,1]
	global_store_dwordx4 v[146:147], v[52:55], off
	global_store_dwordx4 v[146:147], v[40:43], off offset:16
	s_waitcnt vmcnt(20)
	v_pk_fma_f32 v[32:33], v[32:33], 0.5, v[190:191] op_sel_hi:[1,0,1]
	v_pk_fma_f32 v[34:35], v[34:35], 0.5, v[192:193] op_sel_hi:[1,0,1]
	v_pk_fma_f32 v[28:29], v[28:29], 0.5, v[194:195] op_sel_hi:[1,0,1]
	v_pk_fma_f32 v[30:31], v[30:31], 0.5, v[196:197] op_sel_hi:[1,0,1]
	global_store_dwordx4 v[146:147], v[32:35], off offset:512
	global_store_dwordx4 v[146:147], v[28:31], off offset:528
	v_lshl_add_u64 v[146:147], v[146:147], 0, s[98:99]
	s_waitcnt vmcnt(18)
	v_pk_fma_f32 v[36:37], v[36:37], 0.5, v[198:199] op_sel_hi:[1,0,1]
	v_pk_fma_f32 v[38:39], v[38:39], 0.5, v[200:201] op_sel_hi:[1,0,1]
	v_pk_fma_f32 v[24:25], v[24:25], 0.5, v[202:203] op_sel_hi:[1,0,1]
	v_pk_fma_f32 v[26:27], v[26:27], 0.5, v[204:205] op_sel_hi:[1,0,1]
	global_store_dwordx4 v[146:147], v[36:39], off
	global_store_dwordx4 v[146:147], v[24:27], off offset:16
	s_waitcnt vmcnt(16)
	v_pk_fma_f32 v[20:21], v[20:21], 0.5, v[206:207] op_sel_hi:[1,0,1]
	v_pk_fma_f32 v[22:23], v[22:23], 0.5, v[208:209] op_sel_hi:[1,0,1]
	v_pk_fma_f32 v[12:13], v[12:13], 0.5, v[210:211] op_sel_hi:[1,0,1]
	v_pk_fma_f32 v[14:15], v[14:15], 0.5, v[212:213] op_sel_hi:[1,0,1]
	global_store_dwordx4 v[146:147], v[20:23], off offset:512
	global_store_dwordx4 v[146:147], v[12:15], off offset:528
	v_lshl_add_u64 v[146:147], v[146:147], 0, s[98:99]
	s_waitcnt vmcnt(14)
	v_pk_fma_f32 v[16:17], v[16:17], 0.5, v[154:155] op_sel_hi:[1,0,1]
	v_pk_fma_f32 v[18:19], v[18:19], 0.5, v[156:157] op_sel_hi:[1,0,1]
	v_pk_fma_f32 v[8:9], v[8:9], 0.5, v[158:159] op_sel_hi:[1,0,1]
	v_pk_fma_f32 v[10:11], v[10:11], 0.5, v[160:161] op_sel_hi:[1,0,1]
	global_store_dwordx4 v[146:147], v[16:19], off
	global_store_dwordx4 v[146:147], v[8:11], off offset:16
	s_waitcnt vmcnt(12)
	v_pk_fma_f32 v[4:5], v[4:5], 0.5, v[162:163] op_sel_hi:[1,0,1]
	v_pk_fma_f32 v[6:7], v[6:7], 0.5, v[164:165] op_sel_hi:[1,0,1]
	v_pk_fma_f32 v[0:1], v[0:1], 0.5, v[166:167] op_sel_hi:[1,0,1]
	v_pk_fma_f32 v[2:3], v[2:3], 0.5, v[168:169] op_sel_hi:[1,0,1]
	global_store_dwordx4 v[146:147], v[4:7], off offset:512
	global_store_dwordx4 v[146:147], v[0:3], off offset:528
	s_cbranch_vccnz .LBB0_191
	v_readlane_b32 s0, v244, 37
	v_readlane_b32 s1, v244, 38
	s_andn2_b64 vcc, exec, s[0:1]
	s_cbranch_vccnz .LBB0_190
	s_barrier
	s_branch .LBB0_190

;     __device__ bool next(int i, Unit& u) const {
;         const long L = (long)i * G + c; if (L >= nwg) return false;
;         int wgid = (int)L; { const int q = nwg / NXCD, r = nwg % NXCD, xcd = wgid % NXCD, off = wgid / NXCD; wgid = (xcd < r ? xcd * (q + 1) : r * (q + 1) + (xcd - r) * q) + off; }
; __global__ void __launch_bounds__(NTHREADS, 2) fwd_kernel(Args args) {
;     ...
;     if (IN(8)) { pg8::StdOrder S; S.init(T, D, G, bid, D, D, D, 256); pg8::EpiResid E{out, out, 1.f}; pg8::gemm_phase(lds, MG, WOUT, D, D, D, S, E); }
.LBB0_951:
	s_cmp_lt_i32 s90, 9
	s_cselect_b64 s[0:1], -1, 0
	s_and_b64 s[2:3], s[0:1], s[2:3]
	s_andn2_b64 vcc, exec, s[2:3]
	s_cbranch_vccnz .LBB0_976
	s_cmpk_gt_i32 s83, 0x3ff
	v_readfirstlane_b32 s8, v177
	s_cbranch_scc1 .LBB0_976
	s_and_b32 s98, s83, 8
	s_cmp_eq_u32 s98, 0
	s_cbranch_scc1 .Ldly_skip_2
	s_mov_b32 s98, 4

;     __device__ bool next(int i, Unit& u) const {
;         const long L = (long)i * G + c; if (L >= nwg) return false;
;         int wgid = (int)L; { const int q = nwg / NXCD, r = nwg % NXCD, xcd = wgid % NXCD, off = wgid / NXCD; wgid = (xcd < r ? xcd * (q + 1) : r * (q + 1) + (xcd - r) * q) + off; }
;         const int nig = WGM * nN, gid = wgid / nig, fm = gid * WGM, gsz = (nM - fm) < WGM ? (nM - fm) : WGM;
;         u.pm = fm + ((wgid % nig) % gsz); u.pn = (wgid % nig) / gsz;
.Ldly_skip_2:
	s_ashr_i32 s30, s83, 31
	s_lshr_b32 s2, s30, 29
	s_add_i32 s5, s83, s2
	s_and_b32 s2, s5, -8
	s_sub_i32 s6, s83, s2
	s_cmp_gt_i32 s6, -1
	s_cbranch_scc0 .LBB0_955
	s_lshl_b32 s4, s6, 7
	s_cbranch_execz .LBB0_956
	s_branch .LBB0_957

;     __device__ __forceinline__ void operator()(Acc& acc, const Unit& u, int wr, int wc, int fr, int fq) const {
;         const size_t p0 = u.ooff + (size_t)(wr * 64 + fr) * D + wc * 32 + 8 * fq;
; #pragma unroll
;         for (int ai = 0; ai < 2; ++ai)
; #pragma unroll
;             for (int m = 0; m < 4; ++m)
; #pragma unroll
;                 for (int bj = 0; bj < 2; ++bj) {
;                     const size_t p = p0 + (size_t)(ai * 128 + m * 16) * D + bj * 128;
;                     const f32x4 r0 = *(const f32x4*)(R + p), r1 = *(const f32x4*)(R + p + 4);
;                     *(f32x4*)(O + p) = r0 + acc[ai][bj][m][0] * scale; *(f32x4*)(O + p + 4) = r1 + acc[ai][bj][m][1] * scale;
;                 }
.LBB0_972:
	v_lshl_add_u64 v[146:147], s[22:23], 2, v[136:137]
	s_mov_b64 s[22:23], 0x20000
	s_mov_b32 s22, 0x20000
	s_mov_b64 s[22:23], 0x20200
	s_mov_b64 s[22:23], 0x40000
	s_mov_b32 s22, 0x40000
	s_mov_b64 s[22:23], 0x40200
	s_mov_b64 s[22:23], 0x60000
	s_mov_b32 s22, 0x60000
	s_mov_b64 s[22:23], 0x60200
	s_mov_b64 s[22:23], 0x100000
	s_mov_b32 s22, 0x100000
	s_mov_b64 s[22:23], 0x100200
	s_mov_b64 s[22:23], 0x120000
	s_mov_b32 s22, 0x120000
	s_mov_b64 s[22:23], 0x120200
	s_mov_b64 s[22:23], 0x140000
	s_mov_b32 s22, 0x140000
	s_mov_b64 s[22:23], 0x140200
	s_mov_b64 s[22:23], 0x160000
	s_mov_b64 s[22:23], -1
	s_andn2_b64 vcc, exec, s[2:3]
	s_mov_b64 s[98:99], 0x20000
	s_mov_b64 s[100:101], 0xa0000
	v_lshl_add_u64 v[220:221], v[146:147], 0, 0
	global_load_dwordx4 v[152:155], v[146:147], off
	global_load_dwordx4 v[156:159], v[146:147], off offset:16
	global_load_dwordx4 v[160:163], v[146:147], off offset:512
	global_load_dwordx4 v[168:171], v[146:147], off offset:528
	v_lshl_add_u64 v[146:147], v[146:147], 0, s[98:99]
	global_load_dwordx4 v[172:175], v[146:147], off
	global_load_dwordx4 v[180:183], v[146:147], off offset:16
	global_load_dwordx4 v[184:187], v[146:147], off offset:512
	global_load_dwordx4 v[188:191], v[146:147], off offset:528
	v_lshl_add_u64 v[146:147], v[146:147], 0, s[98:99]
	global_load_dwordx4 v[192:195], v[146:147], off
	global_load_dwordx4 v[196:199], v[146:147], off offset:16
	global_load_dwordx4 v[200:203], v[146:147], off offset:512
	global_load_dwordx4 v[204:207], v[146:147], off offset:528
	v_lshl_add_u64 v[146:147], v[146:147], 0, s[98:99]
	global_load_dwordx4 v[208:211], v[146:147], off
	global_load_dwordx4 v[212:215], v[146:147], off offset:16
	s_waitcnt vmcnt(12)
	v_pk_add_f32 v[124:125], v[124:125], v[152:153]
	v_pk_add_f32 v[126:127], v[126:127], v[154:155]
	v_pk_add_f32 v[120:121], v[120:121], v[156:157]
	v_pk_add_f32 v[122:123], v[122:123], v[158:159]
	global_store_dwordx4 v[220:221], v[124:127], off
	global_store_dwordx4 v[220:221], v[120:123], off offset:16
	global_load_dwordx4 v[152:155], v[146:147], off offset:512
	global_load_dwordx4 v[156:159], v[146:147], off offset:528
	v_lshl_add_u64 v[146:147], v[146:147], 0, s[100:101]
	s_waitcnt vmcnt(14)
	v_pk_add_f32 v[112:113], v[112:113], v[160:161]
	v_pk_add_f32 v[114:115], v[114:115], v[162:163]
	v_pk_add_f32 v[104:105], v[104:105], v[168:169]
	v_pk_add_f32 v[106:107], v[106:107], v[170:171]
	global_store_dwordx4 v[220:221], v[112:115], off offset:512
	global_store_dwordx4 v[220:221], v[104:107], off offset:528
	v_lshl_add_u64 v[220:221], v[220:221], 0, s[98:99]
	global_load_dwordx4 v[160:163], v[146:147], off
	global_load_dwordx4 v[168:171], v[146:147], off offset:16
	s_waitcnt vmcnt(16)
	v_pk_add_f32 v[116:117], v[116:117], v[172:173]
	v_pk_add_f32 v[118:119], v[118:119], v[174:175]
	v_pk_add_f32 v[108:109], v[108:109], v[180:181]
	v_pk_add_f32 v[110:111], v[110:111], v[182:183]
	global_store_dwordx4 v[220:221], v[116:119], off
	global_store_dwordx4 v[220:221], v[108:111], off offset:16
	global_load_dwordx4 v[172:175], v[146:147], off offset:512
	global_load_dwordx4 v[180:183], v[146:147], off offset:528
	v_lshl_add_u64 v[146:147], v[146:147], 0, s[98:99]
	s_waitcnt vmcnt(18)
	v_pk_add_f32 v[100:101], v[100:101], v[184:185]
	v_pk_add_f32 v[102:103], v[102:103], v[186:187]
	v_pk_add_f32 v[96:97], v[96:97], v[188:189]
	v_pk_add_f32 v[98:99], v[98:99], v[190:191]
	global_store_dwordx4 v[220:221], v[100:103], off offset:512
	global_store_dwordx4 v[220:221], v[96:99], off offset:528
	v_lshl_add_u64 v[220:221], v[220:221], 0, s[98:99]
	global_load_dwordx4 v[184:187], v[146:147], off
	global_load_dwordx4 v[188:191], v[146:147], off offset:16
	s_waitcnt vmcnt(20)
	v_pk_add_f32 v[92:93], v[92:93], v[192:193]
	v_pk_add_f32 v[94:95], v[94:95], v[194:195]
	v_pk_add_f32 v[88:89], v[88:89], v[196:197]
	v_pk_add_f32 v[90:91], v[90:91], v[198:199]
	global_store_dwordx4 v[220:221], v[92:95], off
	global_store_dwordx4 v[220:221], v[88:91], off offset:16
	global_load_dwordx4 v[192:195], v[146:147], off offset:512
	global_load_dwordx4 v[196:199], v[146:147], off offset:528
	v_lshl_add_u64 v[146:147], v[146:147], 0, s[98:99]
	s_waitcnt vmcnt(22)
;     __device__ __forceinline__ void operator()(Acc& acc, const Unit& u, int wr, int wc, int fr, int fq) const {
;         const size_t p0 = u.ooff + (size_t)(wr * 64 + fr) * D + wc * 32 + 8 * fq;
; #pragma unroll
;         for (int ai = 0; ai < 2; ++ai)
; #pragma unroll
;             for (int m = 0; m < 4; ++m)
; #pragma unroll
;                 for (int bj = 0; bj < 2; ++bj) {
;                     const size_t p = p0 + (size_t)(ai * 128 + m * 16) * D + bj * 128;
;                     const f32x4 r0 = *(const f32x4*)(R + p), r1 = *(const f32x4*)(R + p + 4);
;                     *(f32x4*)(O + p) = r0 + acc[ai][bj][m][0] * scale; *(f32x4*)(O + p + 4) = r1 + acc[ai][bj][m][1] * scale;
;                 }
	v_pk_add_f32 v[84:85], v[84:85], v[200:201]
	v_pk_add_f32 v[86:87], v[86:87], v[202:203]
	v_pk_add_f32 v[80:81], v[80:81], v[204:205]
	v_pk_add_f32 v[82:83], v[82:83], v[206:207]
	global_store_dwordx4 v[220:221], v[84:87], off offset:512
	global_store_dwordx4 v[220:221], v[80:83], off offset:528
	v_lshl_add_u64 v[220:221], v[220:221], 0, s[98:99]
	global_load_dwordx4 v[200:203], v[146:147], off
	global_load_dwordx4 v[204:207], v[146:147], off offset:16
	s_waitcnt vmcnt(24)
	v_pk_add_f32 v[76:77], v[76:77], v[208:209]
	v_pk_add_f32 v[78:79], v[78:79], v[210:211]
	v_pk_add_f32 v[72:73], v[72:73], v[212:213]
	v_pk_add_f32 v[74:75], v[74:75], v[214:215]
	global_store_dwordx4 v[220:221], v[76:79], off
	global_store_dwordx4 v[220:221], v[72:75], off offset:16
	global_load_dwordx4 v[208:211], v[146:147], off offset:512
	global_load_dwordx4 v[212:215], v[146:147], off offset:528
	v_lshl_add_u64 v[146:147], v[146:147], 0, s[98:99]
	s_waitcnt vmcnt(24)
	v_pk_add_f32 v[68:69], v[68:69], v[152:153]
	v_pk_add_f32 v[70:71], v[70:71], v[154:155]
	v_pk_add_f32 v[64:65], v[64:65], v[156:157]
	v_pk_add_f32 v[66:67], v[66:67], v[158:159]
	global_store_dwordx4 v[220:221], v[68:71], off offset:512
	global_store_dwordx4 v[220:221], v[64:67], off offset:528
	v_lshl_add_u64 v[220:221], v[220:221], 0, s[100:101]
	global_load_dwordx4 v[152:155], v[146:147], off
	global_load_dwordx4 v[156:159], v[146:147], off offset:16
	s_waitcnt vmcnt(24)
	v_pk_add_f32 v[60:61], v[60:61], v[160:161]
	v_pk_add_f32 v[62:63], v[62:63], v[162:163]
	v_pk_add_f32 v[56:57], v[56:57], v[168:169]
	v_pk_add_f32 v[58:59], v[58:59], v[170:171]
	global_store_dwordx4 v[220:221], v[60:63], off
	global_store_dwordx4 v[220:221], v[56:59], off offset:16
	global_load_dwordx4 v[160:163], v[146:147], off offset:512
	global_load_dwordx4 v[168:171], v[146:147], off offset:528
	s_waitcnt vmcnt(24)
	v_pk_add_f32 v[52:53], v[52:53], v[172:173]
	v_pk_add_f32 v[54:55], v[54:55], v[174:175]
	v_pk_add_f32 v[48:49], v[48:49], v[180:181]
	v_pk_add_f32 v[50:51], v[50:51], v[182:183]
	global_store_dwordx4 v[220:221], v[52:55], off offset:512
	global_store_dwordx4 v[220:221], v[48:51], off offset:528
	v_lshl_add_u64 v[220:221], v[220:221], 0, s[98:99]
	s_waitcnt vmcnt(22)
	v_pk_add_f32 v[44:45], v[44:45], v[184:185]
	v_pk_add_f32 v[46:47], v[46:47], v[186:187]
	v_pk_add_f32 v[40:41], v[40:41], v[188:189]
	v_pk_add_f32 v[42:43], v[42:43], v[190:191]
	global_store_dwordx4 v[220:221], v[44:47], off
	global_store_dwordx4 v[220:221], v[40:43], off offset:16
	s_waitcnt vmcnt(20)
	v_pk_add_f32 v[36:37], v[36:37], v[192:193]
	v_pk_add_f32 v[38:39], v[38:39], v[194:195]
	v_pk_add_f32 v[32:33], v[32:33], v[196:197]
	v_pk_add_f32 v[34:35], v[34:35], v[198:199]
	global_store_dwordx4 v[220:221], v[36:39], off offset:512
	global_store_dwordx4 v[220:221], v[32:35], off offset:528
	v_lshl_add_u64 v[220:221], v[220:221], 0, s[98:99]
	s_waitcnt vmcnt(18)
	v_pk_add_f32 v[28:29], v[28:29], v[200:201]
	v_pk_add_f32 v[30:31], v[30:31], v[202:203]
	v_pk_add_f32 v[24:25], v[24:25], v[204:205]
	v_pk_add_f32 v[26:27], v[26:27], v[206:207]
	global_store_dwordx4 v[220:221], v[28:31], off
	global_store_dwordx4 v[220:221], v[24:27], off offset:16
	s_waitcnt vmcnt(16)
	v_pk_add_f32 v[20:21], v[20:21], v[208:209]
	v_pk_add_f32 v[22:23], v[22:23], v[210:211]
	v_pk_add_f32 v[16:17], v[16:17], v[212:213]
	v_pk_add_f32 v[18:19], v[18:19], v[214:215]
	global_store_dwordx4 v[220:221], v[20:23], off offset:512
	global_store_dwordx4 v[220:221], v[16:19], off offset:528
	v_lshl_add_u64 v[220:221], v[220:221], 0, s[98:99]
	s_waitcnt vmcnt(14)
	v_pk_add_f32 v[12:13], v[12:13], v[152:153]
	v_pk_add_f32 v[14:15], v[14:15], v[154:155]
	v_pk_add_f32 v[8:9], v[8:9], v[156:157]
	v_pk_add_f32 v[10:11], v[10:11], v[158:159]
	global_store_dwordx4 v[220:221], v[12:15], off
	global_store_dwordx4 v[220:221], v[8:11], off offset:16
	s_waitcnt vmcnt(12)
	v_pk_add_f32 v[4:5], v[4:5], v[160:161]
	v_pk_add_f32 v[6:7], v[6:7], v[162:163]
	v_pk_add_f32 v[0:1], v[0:1], v[168:169]
	v_pk_add_f32 v[2:3], v[2:3], v[170:171]
	global_store_dwordx4 v[220:221], v[4:7], off offset:512
	global_store_dwordx4 v[220:221], v[0:3], off offset:528
	s_cbranch_vccnz .LBB0_961
	s_andn2_b64 vcc, exec, s[4:5]
	s_cbranch_vccnz .LBB0_960
	s_barrier
	s_branch .LBB0_960

;     __device__ bool next(int i, Unit& u) const {
;         const long L = (long)i * G + c; if (L >= nwg) return false;
;         int wgid = (int)L; { const int q = nwg / NXCD, r = nwg % NXCD, xcd = wgid % NXCD, off = wgid / NXCD; wgid = (xcd < r ? xcd * (q + 1) : r * (q + 1) + (xcd - r) * q) + off; }
; __global__ void __launch_bounds__(NTHREADS, 2) fwd_kernel(Args args) {
;     ...
;     if (IN(13)) { pg8::OutOrder S; S.init(T, D, G, bid, 1024, 1024, D, 256); pg8::EpiResid E{out, out, 1.f}; pg8::gemm_phase(lds, Pb, NTb, 1024, 1024, 1024, S, E); }
.LBB0_1218:
	s_cmp_lt_i32 s90, 14
	s_cselect_b64 s[0:1], -1, 0
	s_cmp_gt_i32 s91, 13
	s_cselect_b64 s[2:3], -1, 0
	s_and_b64 s[2:3], s[0:1], s[2:3]
	s_andn2_b64 vcc, exec, s[2:3]
	s_cbranch_vccnz .LBB0_1243
	s_cmpk_gt_i32 s83, 0x3ff
	v_readfirstlane_b32 s10, v177
	s_cbranch_scc1 .LBB0_1243
	s_and_b32 s98, s83, 8
	s_cmp_eq_u32 s98, 0
	s_cbranch_scc1 .Ldly_skip_3
	s_mov_b32 s98, 4

;     __device__ bool next(int i, Unit& u) const {
;         const long L = (long)i * G + c; if (L >= nwg) return false;
;         int wgid = (int)L; { const int q = nwg / NXCD, r = nwg % NXCD, xcd = wgid % NXCD, off = wgid / NXCD; wgid = (xcd < r ? xcd * (q + 1) : r * (q + 1) + (xcd - r) * q) + off; }
;         const int nig = WGM * nN, gid = wgid / nig, fm = gid * WGM, gsz = (nM - fm) < WGM ? (nM - fm) : WGM;
;         u.pm = fm + ((wgid % nig) % gsz); u.pn = (wgid % nig) / gsz;
.Ldly_skip_3:
	s_ashr_i32 s37, s83, 31
	s_lshr_b32 s2, s37, 29
	s_add_i32 s7, s83, s2
	s_and_b32 s2, s7, -8
	s_sub_i32 s8, s83, s2
	s_cmp_gt_i32 s8, -1
	s_cbranch_scc0 .LBB0_1222
	s_lshl_b32 s6, s8, 7
	s_cbranch_execz .LBB0_1223
	s_branch .LBB0_1224

;     __device__ __forceinline__ void operator()(Acc& acc, const Unit& u, int wr, int wc, int fr, int fq) const {
;         const size_t p0 = u.ooff + (size_t)(wr * 64 + fr) * D + wc * 32 + 8 * fq;
; #pragma unroll
;         for (int ai = 0; ai < 2; ++ai)
; #pragma unroll
;             for (int m = 0; m < 4; ++m)
; #pragma unroll
;                 for (int bj = 0; bj < 2; ++bj) {
;                     const size_t p = p0 + (size_t)(ai * 128 + m * 16) * D + bj * 128;
;                     const f32x4 r0 = *(const f32x4*)(R + p), r1 = *(const f32x4*)(R + p + 4);
;                     *(f32x4*)(O + p) = r0 + acc[ai][bj][m][0] * scale; *(f32x4*)(O + p + 4) = r1 + acc[ai][bj][m][1] * scale;
;                 }
.LBB0_1239:
	v_lshl_add_u64 v[146:147], s[38:39], 2, v[136:137]
	s_mov_b32 s33, 0x20000
	s_mov_b64 s[38:39], 0x20000
	s_mov_b64 s[38:39], 0x20200
	s_mov_b32 s33, 0x40000
	s_mov_b64 s[38:39], 0x40000
	s_mov_b64 s[38:39], 0x40200
	s_mov_b32 s33, 0x60000
	s_mov_b64 s[38:39], 0x60000
	s_mov_b64 s[38:39], 0x60200
	s_mov_b32 s33, 0x100000
	s_mov_b64 s[38:39], 0x100000
	s_mov_b64 s[38:39], 0x100200
	s_mov_b64 s[38:39], -1
	s_andn2_b64 vcc, exec, s[2:3]
	s_mov_b64 s[98:99], 0x20000
	s_mov_b64 s[100:101], 0xa0000
	v_lshl_add_u64 v[220:221], v[146:147], 0, 0
	global_load_dwordx4 v[152:155], v[146:147], off
	global_load_dwordx4 v[156:159], v[146:147], off offset:16
	global_load_dwordx4 v[160:163], v[146:147], off offset:512
	global_load_dwordx4 v[168:171], v[146:147], off offset:528
	v_lshl_add_u64 v[146:147], v[146:147], 0, s[98:99]
	global_load_dwordx4 v[172:175], v[146:147], off
	global_load_dwordx4 v[180:183], v[146:147], off offset:16
	global_load_dwordx4 v[184:187], v[146:147], off offset:512
	global_load_dwordx4 v[188:191], v[146:147], off offset:528
	v_lshl_add_u64 v[146:147], v[146:147], 0, s[98:99]
	global_load_dwordx4 v[192:195], v[146:147], off
	global_load_dwordx4 v[196:199], v[146:147], off offset:16
	global_load_dwordx4 v[200:203], v[146:147], off offset:512
	global_load_dwordx4 v[204:207], v[146:147], off offset:528
	v_lshl_add_u64 v[146:147], v[146:147], 0, s[98:99]
	global_load_dwordx4 v[208:211], v[146:147], off
	global_load_dwordx4 v[212:215], v[146:147], off offset:16
	s_waitcnt vmcnt(12)
	v_pk_add_f32 v[124:125], v[124:125], v[152:153]
	v_pk_add_f32 v[126:127], v[126:127], v[154:155]
	v_pk_add_f32 v[120:121], v[120:121], v[156:157]
	v_pk_add_f32 v[122:123], v[122:123], v[158:159]
	global_store_dwordx4 v[220:221], v[124:127], off
	global_store_dwordx4 v[220:221], v[120:123], off offset:16
	global_load_dwordx4 v[152:155], v[146:147], off offset:512
	global_load_dwordx4 v[156:159], v[146:147], off offset:528
	v_lshl_add_u64 v[146:147], v[146:147], 0, s[100:101]
	s_waitcnt vmcnt(14)
	v_pk_add_f32 v[112:113], v[112:113], v[160:161]
	v_pk_add_f32 v[114:115], v[114:115], v[162:163]
	v_pk_add_f32 v[104:105], v[104:105], v[168:169]
	v_pk_add_f32 v[106:107], v[106:107], v[170:171]
	global_store_dwordx4 v[220:221], v[112:115], off offset:512
	global_store_dwordx4 v[220:221], v[104:107], off offset:528
	v_lshl_add_u64 v[220:221], v[220:221], 0, s[98:99]
	global_load_dwordx4 v[160:163], v[146:147], off
	global_load_dwordx4 v[168:171], v[146:147], off offset:16
	s_waitcnt vmcnt(16)
	v_pk_add_f32 v[116:117], v[116:117], v[172:173]
	v_pk_add_f32 v[118:119], v[118:119], v[174:175]
	v_pk_add_f32 v[108:109], v[108:109], v[180:181]
	v_pk_add_f32 v[110:111], v[110:111], v[182:183]
	global_store_dwordx4 v[220:221], v[116:119], off
	global_store_dwordx4 v[220:221], v[108:111], off offset:16
	global_load_dwordx4 v[172:175], v[146:147], off offset:512
	global_load_dwordx4 v[180:183], v[146:147], off offset:528
	v_lshl_add_u64 v[146:147], v[146:147], 0, s[98:99]
	s_waitcnt vmcnt(18)
	v_pk_add_f32 v[100:101], v[100:101], v[184:185]
	v_pk_add_f32 v[102:103], v[102:103], v[186:187]
	v_pk_add_f32 v[96:97], v[96:97], v[188:189]
	v_pk_add_f32 v[98:99], v[98:99], v[190:191]
	global_store_dwordx4 v[220:221], v[100:103], off offset:512
	global_store_dwordx4 v[220:221], v[96:99], off offset:528
	v_lshl_add_u64 v[220:221], v[220:221], 0, s[98:99]
	global_load_dwordx4 v[184:187], v[146:147], off
	global_load_dwordx4 v[188:191], v[146:147], off offset:16
	s_waitcnt vmcnt(20)
	v_pk_add_f32 v[92:93], v[92:93], v[192:193]
	v_pk_add_f32 v[94:95], v[94:95], v[194:195]
	v_pk_add_f32 v[88:89], v[88:89], v[196:197]
	v_pk_add_f32 v[90:91], v[90:91], v[198:199]
	global_store_dwordx4 v[220:221], v[92:95], off
	global_store_dwordx4 v[220:221], v[88:91], off offset:16
	global_load_dwordx4 v[192:195], v[146:147], off offset:512
	global_load_dwordx4 v[196:199], v[146:147], off offset:528
	v_lshl_add_u64 v[146:147], v[146:147], 0, s[98:99]
	s_waitcnt vmcnt(22)
;     __device__ __forceinline__ void operator()(Acc& acc, const Unit& u, int wr, int wc, int fr, int fq) const {
;         const size_t p0 = u.ooff + (size_t)(wr * 64 + fr) * D + wc * 32 + 8 * fq;
; #pragma unroll
;         for (int ai = 0; ai < 2; ++ai)
; #pragma unroll
;             for (int m = 0; m < 4; ++m)
; #pragma unroll
;                 for (int bj = 0; bj < 2; ++bj) {
;                     const size_t p = p0 + (size_t)(ai * 128 + m * 16) * D + bj * 128;
;                     const f32x4 r0 = *(const f32x4*)(R + p), r1 = *(const f32x4*)(R + p + 4);
;                     *(f32x4*)(O + p) = r0 + acc[ai][bj][m][0] * scale; *(f32x4*)(O + p + 4) = r1 + acc[ai][bj][m][1] * scale;
;                 }
	v_pk_add_f32 v[84:85], v[84:85], v[200:201]
	v_pk_add_f32 v[86:87], v[86:87], v[202:203]
	v_pk_add_f32 v[80:81], v[80:81], v[204:205]
	v_pk_add_f32 v[82:83], v[82:83], v[206:207]
	global_store_dwordx4 v[220:221], v[84:87], off offset:512
	global_store_dwordx4 v[220:221], v[80:83], off offset:528
	v_lshl_add_u64 v[220:221], v[220:221], 0, s[98:99]
	global_load_dwordx4 v[200:203], v[146:147], off
	global_load_dwordx4 v[204:207], v[146:147], off offset:16
	s_waitcnt vmcnt(24)
	v_pk_add_f32 v[76:77], v[76:77], v[208:209]
	v_pk_add_f32 v[78:79], v[78:79], v[210:211]
	v_pk_add_f32 v[72:73], v[72:73], v[212:213]
	v_pk_add_f32 v[74:75], v[74:75], v[214:215]
	global_store_dwordx4 v[220:221], v[76:79], off
	global_store_dwordx4 v[220:221], v[72:75], off offset:16
	global_load_dwordx4 v[208:211], v[146:147], off offset:512
	global_load_dwordx4 v[212:215], v[146:147], off offset:528
	v_lshl_add_u64 v[146:147], v[146:147], 0, s[98:99]
	s_waitcnt vmcnt(24)
	v_pk_add_f32 v[68:69], v[68:69], v[152:153]
	v_pk_add_f32 v[70:71], v[70:71], v[154:155]
	v_pk_add_f32 v[64:65], v[64:65], v[156:157]
	v_pk_add_f32 v[66:67], v[66:67], v[158:159]
	global_store_dwordx4 v[220:221], v[68:71], off offset:512
	global_store_dwordx4 v[220:221], v[64:67], off offset:528
	v_lshl_add_u64 v[220:221], v[220:221], 0, s[100:101]
	global_load_dwordx4 v[152:155], v[146:147], off
	global_load_dwordx4 v[156:159], v[146:147], off offset:16
	s_waitcnt vmcnt(24)
	v_pk_add_f32 v[60:61], v[60:61], v[160:161]
	v_pk_add_f32 v[62:63], v[62:63], v[162:163]
	v_pk_add_f32 v[56:57], v[56:57], v[168:169]
	v_pk_add_f32 v[58:59], v[58:59], v[170:171]
	global_store_dwordx4 v[220:221], v[60:63], off
	global_store_dwordx4 v[220:221], v[56:59], off offset:16
	global_load_dwordx4 v[160:163], v[146:147], off offset:512
	global_load_dwordx4 v[168:171], v[146:147], off offset:528
	s_waitcnt vmcnt(24)
	v_pk_add_f32 v[52:53], v[52:53], v[172:173]
	v_pk_add_f32 v[54:55], v[54:55], v[174:175]
	v_pk_add_f32 v[48:49], v[48:49], v[180:181]
	v_pk_add_f32 v[50:51], v[50:51], v[182:183]
	global_store_dwordx4 v[220:221], v[52:55], off offset:512
	global_store_dwordx4 v[220:221], v[48:51], off offset:528
	v_lshl_add_u64 v[220:221], v[220:221], 0, s[98:99]
	s_waitcnt vmcnt(22)
	v_pk_add_f32 v[44:45], v[44:45], v[184:185]
	v_pk_add_f32 v[46:47], v[46:47], v[186:187]
	v_pk_add_f32 v[40:41], v[40:41], v[188:189]
	v_pk_add_f32 v[42:43], v[42:43], v[190:191]
	global_store_dwordx4 v[220:221], v[44:47], off
	global_store_dwordx4 v[220:221], v[40:43], off offset:16
	s_waitcnt vmcnt(20)
	v_pk_add_f32 v[36:37], v[36:37], v[192:193]
	v_pk_add_f32 v[38:39], v[38:39], v[194:195]
	v_pk_add_f32 v[32:33], v[32:33], v[196:197]
	v_pk_add_f32 v[34:35], v[34:35], v[198:199]
	global_store_dwordx4 v[220:221], v[36:39], off offset:512
	global_store_dwordx4 v[220:221], v[32:35], off offset:528
	v_lshl_add_u64 v[220:221], v[220:221], 0, s[98:99]
	s_waitcnt vmcnt(18)
	v_pk_add_f32 v[28:29], v[28:29], v[200:201]
	v_pk_add_f32 v[30:31], v[30:31], v[202:203]
	v_pk_add_f32 v[24:25], v[24:25], v[204:205]
	v_pk_add_f32 v[26:27], v[26:27], v[206:207]
	global_store_dwordx4 v[220:221], v[28:31], off
	global_store_dwordx4 v[220:221], v[24:27], off offset:16
	s_waitcnt vmcnt(16)
	v_pk_add_f32 v[20:21], v[20:21], v[208:209]
	v_pk_add_f32 v[22:23], v[22:23], v[210:211]
	v_pk_add_f32 v[16:17], v[16:17], v[212:213]
	v_pk_add_f32 v[18:19], v[18:19], v[214:215]
	global_store_dwordx4 v[220:221], v[20:23], off offset:512
	global_store_dwordx4 v[220:221], v[16:19], off offset:528
	v_lshl_add_u64 v[220:221], v[220:221], 0, s[98:99]
	s_waitcnt vmcnt(14)
	v_pk_add_f32 v[12:13], v[12:13], v[152:153]
	v_pk_add_f32 v[14:15], v[14:15], v[154:155]
	v_pk_add_f32 v[8:9], v[8:9], v[156:157]
	v_pk_add_f32 v[10:11], v[10:11], v[158:159]
	global_store_dwordx4 v[220:221], v[12:15], off
	global_store_dwordx4 v[220:221], v[8:11], off offset:16
	s_waitcnt vmcnt(12)
	v_pk_add_f32 v[4:5], v[4:5], v[160:161]
	v_pk_add_f32 v[6:7], v[6:7], v[162:163]
	v_pk_add_f32 v[0:1], v[0:1], v[168:169]
	v_pk_add_f32 v[2:3], v[2:3], v[170:171]
	global_store_dwordx4 v[220:221], v[4:7], off offset:512
	global_store_dwordx4 v[220:221], v[0:3], off offset:528
	s_cbranch_vccnz .LBB0_1228
	s_andn2_b64 vcc, exec, s[6:7]
	s_cbranch_vccnz .LBB0_1227
	s_barrier
	s_branch .LBB0_1227

;     __device__ bool next(int i, Unit& u) const {
;         const long L = (long)i * G + c; if (L >= nwg) return false;
;         int wgid = (int)L; { const int q = nwg / NXCD, r = nwg % NXCD, xcd = wgid % NXCD, off = wgid / NXCD; wgid = (xcd < r ? xcd * (q + 1) : r * (q + 1) + (xcd - r) * q) + off; }
; __global__ void __launch_bounds__(NTHREADS, 2) fwd_kernel(Args args) {
;     ...
;     if (IN(16)) { pg8::StdOrder S; S.init(T, D, G, bid, DFF, DFF, D, 256); pg8::EpiResid E{out, out, 0.5f}; pg8::gemm_phase(lds, HB, WDN2, DFF, DFF, DFF, S, E); }
.LBB0_1430:
	s_cmp_lt_i32 s90, 17
	s_cselect_b64 s[0:1], -1, 0
	s_and_b64 s[2:3], s[0:1], s[2:3]
	s_andn2_b64 vcc, exec, s[2:3]
	s_cbranch_vccnz .LBB0_1455
	s_cmpk_gt_i32 s83, 0x3ff
	v_readfirstlane_b32 s8, v177
	s_cbranch_scc1 .LBB0_1455
	s_and_b32 s98, s83, 8
	s_cmp_eq_u32 s98, 0
	s_cbranch_scc1 .Ldly_skip_4
	s_mov_b32 s98, 4

;     __device__ bool next(int i, Unit& u) const {
;         const long L = (long)i * G + c; if (L >= nwg) return false;
;         int wgid = (int)L; { const int q = nwg / NXCD, r = nwg % NXCD, xcd = wgid % NXCD, off = wgid / NXCD; wgid = (xcd < r ? xcd * (q + 1) : r * (q + 1) + (xcd - r) * q) + off; }
;         const int nig = WGM * nN, gid = wgid / nig, fm = gid * WGM, gsz = (nM - fm) < WGM ? (nM - fm) : WGM;
;         u.pm = fm + ((wgid % nig) % gsz); u.pn = (wgid % nig) / gsz;
.Ldly_skip_4:
	s_ashr_i32 s37, s83, 31
	s_lshr_b32 s2, s37, 29
	s_add_i32 s6, s83, s2
	s_and_b32 s2, s6, -8
	s_sub_i32 s5, s83, s2
	s_cmp_gt_i32 s5, -1
	s_cbranch_scc0 .LBB0_1434
	s_lshl_b32 s4, s5, 7
	s_ashr_i32 s2, s6, 3
	s_cbranch_execz .LBB0_1435
	s_branch .LBB0_1436

;     __device__ __forceinline__ void operator()(Acc& acc, const Unit& u, int wr, int wc, int fr, int fq) const {
;         const size_t p0 = u.ooff + (size_t)(wr * 64 + fr) * D + wc * 32 + 8 * fq;
; #pragma unroll
;         for (int ai = 0; ai < 2; ++ai)
; #pragma unroll
;             for (int m = 0; m < 4; ++m)
; #pragma unroll
;                 for (int bj = 0; bj < 2; ++bj) {
;                     const size_t p = p0 + (size_t)(ai * 128 + m * 16) * D + bj * 128;
;                     const f32x4 r0 = *(const f32x4*)(R + p), r1 = *(const f32x4*)(R + p + 4);
;                     *(f32x4*)(O + p) = r0 + acc[ai][bj][m][0] * scale; *(f32x4*)(O + p + 4) = r1 + acc[ai][bj][m][1] * scale;
;                 }
.LBB0_1451:
	v_lshl_add_u64 v[146:147], s[50:51], 2, v[136:137]
	s_mov_b32 s33, 0x20000
	s_mov_b64 s[50:51], 0x20000
	s_mov_b64 s[50:51], 0x20200
	s_mov_b64 s[50:51], 0x160000
	s_mov_b64 s[50:51], -1
	s_andn2_b64 vcc, exec, s[2:3]
	s_mov_b64 s[98:99], 0x20000
	s_mov_b64 s[100:101], 0xa0000
	v_lshl_add_u64 v[214:215], v[146:147], 0, 0
	global_load_dwordx4 v[152:155], v[146:147], off
	global_load_dwordx4 v[156:159], v[146:147], off offset:16
	global_load_dwordx4 v[160:163], v[146:147], off offset:512
	global_load_dwordx4 v[164:167], v[146:147], off offset:528
	v_lshl_add_u64 v[146:147], v[146:147], 0, s[98:99]
	global_load_dwordx4 v[168:171], v[146:147], off
	global_load_dwordx4 v[172:175], v[146:147], off offset:16
	global_load_dwordx4 v[178:181], v[146:147], off offset:512
	global_load_dwordx4 v[182:185], v[146:147], off offset:528
	v_lshl_add_u64 v[146:147], v[146:147], 0, s[98:99]
	global_load_dwordx4 v[186:189], v[146:147], off
	global_load_dwordx4 v[190:193], v[146:147], off offset:16
	global_load_dwordx4 v[194:197], v[146:147], off offset:512
	global_load_dwordx4 v[198:201], v[146:147], off offset:528
	v_lshl_add_u64 v[146:147], v[146:147], 0, s[98:99]
	global_load_dwordx4 v[202:205], v[146:147], off
	global_load_dwordx4 v[206:209], v[146:147], off offset:16
	s_waitcnt vmcnt(12)
	v_pk_fma_f32 v[124:125], v[124:125], 0.5, v[152:153] op_sel_hi:[1,0,1]
	v_pk_fma_f32 v[126:127], v[126:127], 0.5, v[154:155] op_sel_hi:[1,0,1]
	v_pk_fma_f32 v[120:121], v[120:121], 0.5, v[156:157] op_sel_hi:[1,0,1]
	v_pk_fma_f32 v[122:123], v[122:123], 0.5, v[158:159] op_sel_hi:[1,0,1]
	global_store_dwordx4 v[214:215], v[124:127], off
	global_store_dwordx4 v[214:215], v[120:123], off offset:16
	global_load_dwordx4 v[152:155], v[146:147], off offset:512
	global_load_dwordx4 v[156:159], v[146:147], off offset:528
	v_lshl_add_u64 v[146:147], v[146:147], 0, s[100:101]
	s_waitcnt vmcnt(14)
	v_pk_fma_f32 v[116:117], v[116:117], 0.5, v[160:161] op_sel_hi:[1,0,1]
	v_pk_fma_f32 v[118:119], v[118:119], 0.5, v[162:163] op_sel_hi:[1,0,1]
	v_pk_fma_f32 v[112:113], v[112:113], 0.5, v[164:165] op_sel_hi:[1,0,1]
	v_pk_fma_f32 v[114:115], v[114:115], 0.5, v[166:167] op_sel_hi:[1,0,1]
	global_store_dwordx4 v[214:215], v[116:119], off offset:512
	global_store_dwordx4 v[214:215], v[112:115], off offset:528
	v_lshl_add_u64 v[214:215], v[214:215], 0, s[98:99]
	global_load_dwordx4 v[160:163], v[146:147], off
	global_load_dwordx4 v[164:167], v[146:147], off offset:16
	s_waitcnt vmcnt(16)
	v_pk_fma_f32 v[108:109], v[108:109], 0.5, v[168:169] op_sel_hi:[1,0,1]
	v_pk_fma_f32 v[110:111], v[110:111], 0.5, v[170:171] op_sel_hi:[1,0,1]
	v_pk_fma_f32 v[104:105], v[104:105], 0.5, v[172:173] op_sel_hi:[1,0,1]
	v_pk_fma_f32 v[106:107], v[106:107], 0.5, v[174:175] op_sel_hi:[1,0,1]
	global_store_dwordx4 v[214:215], v[108:111], off
	global_store_dwordx4 v[214:215], v[104:107], off offset:16
	global_load_dwordx4 v[168:171], v[146:147], off offset:512
	global_load_dwordx4 v[172:175], v[146:147], off offset:528
	v_lshl_add_u64 v[146:147], v[146:147], 0, s[98:99]
	s_waitcnt vmcnt(18)
	v_pk_fma_f32 v[100:101], v[100:101], 0.5, v[178:179] op_sel_hi:[1,0,1]
	v_pk_fma_f32 v[102:103], v[102:103], 0.5, v[180:181] op_sel_hi:[1,0,1]
	v_pk_fma_f32 v[96:97], v[96:97], 0.5, v[182:183] op_sel_hi:[1,0,1]
	v_pk_fma_f32 v[98:99], v[98:99], 0.5, v[184:185] op_sel_hi:[1,0,1]
	global_store_dwordx4 v[214:215], v[100:103], off offset:512
	global_store_dwordx4 v[214:215], v[96:99], off offset:528
	v_lshl_add_u64 v[214:215], v[214:215], 0, s[98:99]
	global_load_dwordx4 v[178:181], v[146:147], off
	global_load_dwordx4 v[182:185], v[146:147], off offset:16
	s_waitcnt vmcnt(20)
	v_pk_fma_f32 v[92:93], v[92:93], 0.5, v[186:187] op_sel_hi:[1,0,1]
	v_pk_fma_f32 v[94:95], v[94:95], 0.5, v[188:189] op_sel_hi:[1,0,1]
	v_pk_fma_f32 v[88:89], v[88:89], 0.5, v[190:191] op_sel_hi:[1,0,1]
	v_pk_fma_f32 v[90:91], v[90:91], 0.5, v[192:193] op_sel_hi:[1,0,1]
	global_store_dwordx4 v[214:215], v[92:95], off
	global_store_dwordx4 v[214:215], v[88:91], off offset:16
	global_load_dwordx4 v[186:189], v[146:147], off offset:512
	global_load_dwordx4 v[190:193], v[146:147], off offset:528
	v_lshl_add_u64 v[146:147], v[146:147], 0, s[98:99]
	s_waitcnt vmcnt(22)
	v_pk_fma_f32 v[84:85], v[84:85], 0.5, v[194:195] op_sel_hi:[1,0,1]
	v_pk_fma_f32 v[86:87], v[86:87], 0.5, v[196:197] op_sel_hi:[1,0,1]
	v_pk_fma_f32 v[80:81], v[80:81], 0.5, v[198:199] op_sel_hi:[1,0,1]
	v_pk_fma_f32 v[82:83], v[82:83], 0.5, v[200:201] op_sel_hi:[1,0,1]
	global_store_dwordx4 v[214:215], v[84:87], off offset:512
	global_store_dwordx4 v[214:215], v[80:83], off offset:528
	v_lshl_add_u64 v[214:215], v[214:215], 0, s[98:99]
	global_load_dwordx4 v[194:197], v[146:147], off
	global_load_dwordx4 v[198:201], v[146:147], off offset:16
	s_waitcnt vmcnt(24)
;     __device__ __forceinline__ void operator()(Acc& acc, const Unit& u, int wr, int wc, int fr, int fq) const {
;         const size_t p0 = u.ooff + (size_t)(wr * 64 + fr) * D + wc * 32 + 8 * fq;
; #pragma unroll
;         for (int ai = 0; ai < 2; ++ai)
; #pragma unroll
;             for (int m = 0; m < 4; ++m)
; #pragma unroll
;                 for (int bj = 0; bj < 2; ++bj) {
;                     const size_t p = p0 + (size_t)(ai * 128 + m * 16) * D + bj * 128;
;                     const f32x4 r0 = *(const f32x4*)(R + p), r1 = *(const f32x4*)(R + p + 4);
;                     *(f32x4*)(O + p) = r0 + acc[ai][bj][m][0] * scale; *(f32x4*)(O + p + 4) = r1 + acc[ai][bj][m][1] * scale;
;                 }
	v_pk_fma_f32 v[76:77], v[76:77], 0.5, v[202:203] op_sel_hi:[1,0,1]
	v_pk_fma_f32 v[78:79], v[78:79], 0.5, v[204:205] op_sel_hi:[1,0,1]
	v_pk_fma_f32 v[72:73], v[72:73], 0.5, v[206:207] op_sel_hi:[1,0,1]
	v_pk_fma_f32 v[74:75], v[74:75], 0.5, v[208:209] op_sel_hi:[1,0,1]
	global_store_dwordx4 v[214:215], v[76:79], off
	global_store_dwordx4 v[214:215], v[72:75], off offset:16
	global_load_dwordx4 v[202:205], v[146:147], off offset:512
	global_load_dwordx4 v[206:209], v[146:147], off offset:528
	v_lshl_add_u64 v[146:147], v[146:147], 0, s[98:99]
	s_waitcnt vmcnt(24)
	v_pk_fma_f32 v[68:69], v[68:69], 0.5, v[152:153] op_sel_hi:[1,0,1]
	v_pk_fma_f32 v[70:71], v[70:71], 0.5, v[154:155] op_sel_hi:[1,0,1]
	v_pk_fma_f32 v[64:65], v[64:65], 0.5, v[156:157] op_sel_hi:[1,0,1]
	v_pk_fma_f32 v[66:67], v[66:67], 0.5, v[158:159] op_sel_hi:[1,0,1]
	global_store_dwordx4 v[214:215], v[68:71], off offset:512
	global_store_dwordx4 v[214:215], v[64:67], off offset:528
	v_lshl_add_u64 v[214:215], v[214:215], 0, s[100:101]
	global_load_dwordx4 v[152:155], v[146:147], off
	global_load_dwordx4 v[156:159], v[146:147], off offset:16
	s_waitcnt vmcnt(24)
	v_pk_fma_f32 v[60:61], v[60:61], 0.5, v[160:161] op_sel_hi:[1,0,1]
	v_pk_fma_f32 v[62:63], v[62:63], 0.5, v[162:163] op_sel_hi:[1,0,1]
	v_pk_fma_f32 v[56:57], v[56:57], 0.5, v[164:165] op_sel_hi:[1,0,1]
	v_pk_fma_f32 v[58:59], v[58:59], 0.5, v[166:167] op_sel_hi:[1,0,1]
	global_store_dwordx4 v[214:215], v[60:63], off
	global_store_dwordx4 v[214:215], v[56:59], off offset:16
	global_load_dwordx4 v[160:163], v[146:147], off offset:512
	global_load_dwordx4 v[164:167], v[146:147], off offset:528
	s_waitcnt vmcnt(24)
	v_pk_fma_f32 v[52:53], v[52:53], 0.5, v[168:169] op_sel_hi:[1,0,1]
	v_pk_fma_f32 v[54:55], v[54:55], 0.5, v[170:171] op_sel_hi:[1,0,1]
	v_pk_fma_f32 v[48:49], v[48:49], 0.5, v[172:173] op_sel_hi:[1,0,1]
	v_pk_fma_f32 v[50:51], v[50:51], 0.5, v[174:175] op_sel_hi:[1,0,1]
	global_store_dwordx4 v[214:215], v[52:55], off offset:512
	global_store_dwordx4 v[214:215], v[48:51], off offset:528
	v_lshl_add_u64 v[214:215], v[214:215], 0, s[98:99]
	s_waitcnt vmcnt(22)
	v_pk_fma_f32 v[44:45], v[44:45], 0.5, v[178:179] op_sel_hi:[1,0,1]
	v_pk_fma_f32 v[46:47], v[46:47], 0.5, v[180:181] op_sel_hi:[1,0,1]
	v_pk_fma_f32 v[40:41], v[40:41], 0.5, v[182:183] op_sel_hi:[1,0,1]
	v_pk_fma_f32 v[42:43], v[42:43], 0.5, v[184:185] op_sel_hi:[1,0,1]
	global_store_dwordx4 v[214:215], v[44:47], off
	global_store_dwordx4 v[214:215], v[40:43], off offset:16
	s_waitcnt vmcnt(20)
	v_pk_fma_f32 v[36:37], v[36:37], 0.5, v[186:187] op_sel_hi:[1,0,1]
	v_pk_fma_f32 v[38:39], v[38:39], 0.5, v[188:189] op_sel_hi:[1,0,1]
	v_pk_fma_f32 v[32:33], v[32:33], 0.5, v[190:191] op_sel_hi:[1,0,1]
	v_pk_fma_f32 v[34:35], v[34:35], 0.5, v[192:193] op_sel_hi:[1,0,1]
	global_store_dwordx4 v[214:215], v[36:39], off offset:512
	global_store_dwordx4 v[214:215], v[32:35], off offset:528
	v_lshl_add_u64 v[214:215], v[214:215], 0, s[98:99]
	s_waitcnt vmcnt(18)
	v_pk_fma_f32 v[28:29], v[28:29], 0.5, v[194:195] op_sel_hi:[1,0,1]
	v_pk_fma_f32 v[30:31], v[30:31], 0.5, v[196:197] op_sel_hi:[1,0,1]
	v_pk_fma_f32 v[24:25], v[24:25], 0.5, v[198:199] op_sel_hi:[1,0,1]
	v_pk_fma_f32 v[26:27], v[26:27], 0.5, v[200:201] op_sel_hi:[1,0,1]
	global_store_dwordx4 v[214:215], v[28:31], off
	global_store_dwordx4 v[214:215], v[24:27], off offset:16
	s_waitcnt vmcnt(16)
	v_pk_fma_f32 v[20:21], v[20:21], 0.5, v[202:203] op_sel_hi:[1,0,1]
	v_pk_fma_f32 v[22:23], v[22:23], 0.5, v[204:205] op_sel_hi:[1,0,1]
	v_pk_fma_f32 v[16:17], v[16:17], 0.5, v[206:207] op_sel_hi:[1,0,1]
	v_pk_fma_f32 v[18:19], v[18:19], 0.5, v[208:209] op_sel_hi:[1,0,1]
	global_store_dwordx4 v[214:215], v[20:23], off offset:512
	global_store_dwordx4 v[214:215], v[16:19], off offset:528
	v_lshl_add_u64 v[214:215], v[214:215], 0, s[98:99]
	s_waitcnt vmcnt(14)
	v_pk_fma_f32 v[12:13], v[12:13], 0.5, v[152:153] op_sel_hi:[1,0,1]
	v_pk_fma_f32 v[14:15], v[14:15], 0.5, v[154:155] op_sel_hi:[1,0,1]
	v_pk_fma_f32 v[8:9], v[8:9], 0.5, v[156:157] op_sel_hi:[1,0,1]
	v_pk_fma_f32 v[10:11], v[10:11], 0.5, v[158:159] op_sel_hi:[1,0,1]
	global_store_dwordx4 v[214:215], v[12:15], off
	global_store_dwordx4 v[214:215], v[8:11], off offset:16
	s_waitcnt vmcnt(12)
	v_pk_fma_f32 v[4:5], v[4:5], 0.5, v[160:161] op_sel_hi:[1,0,1]
	v_pk_fma_f32 v[6:7], v[6:7], 0.5, v[162:163] op_sel_hi:[1,0,1]
	v_pk_fma_f32 v[0:1], v[0:1], 0.5, v[164:165] op_sel_hi:[1,0,1]
	v_pk_fma_f32 v[2:3], v[2:3], 0.5, v[166:167] op_sel_hi:[1,0,1]
	global_store_dwordx4 v[214:215], v[4:7], off offset:512
	global_store_dwordx4 v[214:215], v[0:3], off offset:528
	s_cbranch_vccnz .LBB0_1440
	s_andn2_b64 vcc, exec, s[4:5]
	s_cbranch_vccnz .LBB0_1439
	s_barrier
	s_branch .LBB0_1439

; __global__ void __launch_bounds__(NTHREADS, 2) fwd_kernel(Args args) {
	.amdhsa_kernel _Z10fwd_kernel4Args
		.amdhsa_group_segment_fixed_size 0
		.amdhsa_private_segment_fixed_size 0
		.amdhsa_kernarg_size 512
		.amdhsa_user_sgpr_count 2
		.amdhsa_user_sgpr_dispatch_ptr 0
		.amdhsa_user_sgpr_queue_ptr 0
		.amdhsa_user_sgpr_kernarg_segment_ptr 1
		.amdhsa_user_sgpr_dispatch_id 0
		.amdhsa_user_sgpr_kernarg_preload_length 0
		.amdhsa_user_sgpr_kernarg_preload_offset 0
		.amdhsa_user_sgpr_private_segment_size 0
		.amdhsa_uses_dynamic_stack 0
		.amdhsa_enable_private_segment 0
		.amdhsa_system_sgpr_workgroup_id_x 1
		.amdhsa_system_sgpr_workgroup_id_y 0
		.amdhsa_system_sgpr_workgroup_id_z 0
		.amdhsa_system_sgpr_workgroup_info 0
		.amdhsa_system_vgpr_workitem_id 2
		.amdhsa_next_free_vgpr 248
		.amdhsa_next_free_sgpr 102
		.amdhsa_accum_offset 248
		.amdhsa_reserve_vcc 1
		.amdhsa_float_round_mode_32 0
		.amdhsa_float_round_mode_16_64 0
		.amdhsa_float_denorm_mode_32 3
		.amdhsa_float_denorm_mode_16_64 3
		.amdhsa_dx10_clamp 1
		.amdhsa_ieee_mode 1
		.amdhsa_fp16_overflow 0
		.amdhsa_tg_split 0
		.amdhsa_exception_fp_ieee_invalid_op 0
		.amdhsa_exception_fp_denorm_src 0
		.amdhsa_exception_fp_ieee_div_zero 0
		.amdhsa_exception_fp_ieee_overflow 0
		.amdhsa_exception_fp_ieee_underflow 0
		.amdhsa_exception_fp_ieee_inexact 0
		.amdhsa_exception_int_div_zero 0
	.end_amdhsa_kernel

; __global__ void __launch_bounds__(NTHREADS, 2) fwd_kernel(Args args) {
amdhsa.kernels:
  - .agpr_count:     0
    .args:
      - .offset:         0
        .size:           256
        .value_kind:     by_value
      - .offset:         256
        .size:           4
        .value_kind:     hidden_block_count_x
      - .offset:         260
        .size:           4
        .value_kind:     hidden_block_count_y
      - .offset:         264
        .size:           4
        .value_kind:     hidden_block_count_z
      - .offset:         268
        .size:           2
        .value_kind:     hidden_group_size_x
      - .offset:         270
        .size:           2
        .value_kind:     hidden_group_size_y
      - .offset:         272
        .size:           2
        .value_kind:     hidden_group_size_z
      - .offset:         274
        .size:           2
        .value_kind:     hidden_remainder_x
      - .offset:         276
        .size:           2
        .value_kind:     hidden_remainder_y
      - .offset:         278
        .size:           2
        .value_kind:     hidden_remainder_z
      - .offset:         296
        .size:           8
        .value_kind:     hidden_global_offset_x
      - .offset:         304
        .size:           8
        .value_kind:     hidden_global_offset_y
      - .offset:         312
        .size:           8
        .value_kind:     hidden_global_offset_z
      - .offset:         320
        .size:           2
        .value_kind:     hidden_grid_dims
      - .offset:         344
        .size:           8
        .value_kind:     hidden_multigrid_sync_arg
      - .offset:         376
        .size:           4
        .value_kind:     hidden_dynamic_lds_size
    .group_segment_fixed_size: 0
    .kernarg_segment_align: 8
    .kernarg_segment_size: 512
    .language:       OpenCL C
    .language_version:
      - 2
      - 0
    .max_flat_workgroup_size: 512
    .name:           _Z10fwd_kernel4Args
    .private_segment_fixed_size: 0
    .sgpr_count:     108
    .sgpr_spill_count: 137
    .symbol:         _Z10fwd_kernel4Args.kd
    .uniform_work_group_size: 1
    .uses_dynamic_stack: false
    .vgpr_count:     248
    .vgpr_spill_count: 0
    .wavefront_size: 64
